# v087 + scan/ssm/attention made batch-local (XCD x works on batch x; per-XCD attention work counters; scan chunk states relocated into the XCD's own rmsnorm rows): k1->k2 barriers XCD-local too; 11 XCD
# speedup vs baseline: 1.0281x; 1.0086x over previous
;     __device__ __forceinline__ unsigned char* ws() const { return *(const __attribute__((address_space(4))) ucptr_t*)(p + 264); }
; __device__ __forceinline__ void rwkv_p3(const KA& A, const Ctx& F) {
;     ...
;     for (int it4 = F.bid; it4 < RW_ITEMS / 4; it4 += F.G) {
;         const int item = (RW_ITEMS / 4 - 1 - it4) * 4 + (w >> 1); const int j = item & 63, h = (item >> 6) % 6, b = item / 384;
;         const size_t row0 = (size_t)b * SEQ + 64 * j;
;         const int t = 32 * tb2 + r32;
;         const bf16* qd = PS + (row0 + t) * PSW + C_RW + h * 64; const bf16* yd = qd + 384; const bf16* ed = qd + 768; const bf16* EM = (const bf16*)(F.ws + WS_REM) + (size_t)item * 4096 + t * 64;
;         const bf16* HS = (const bf16*)(F.ws + WS_RHS) + (size_t)item * 4096;
;         bf16x8_t qf[4], hf[2][4];
; #pragma unroll
;         for (int s = 0; s < 4; ++s) { qf[s] = *(const bf16x8_t*)(qd + 16 * s + 8 * hh); hf[0][s] = *(const bf16x8_t*)(HS + ((s * 64 + lane) << 3)); hf[1][s] = *(const bf16x8_t*)(HS + (((4 + s) * 64 + lane) << 3)); }
;         f32x16 y[2]; v2u em[2][4], ea[2][4], yq[2][4]; v4u yw[2][2], mw[2][2], aw[2][2];
; #pragma unroll
;         for (int it = 0; it < 2; ++it)
; #pragma unroll
;             for (int k2 = 0; k2 < 2; ++k2) { const int i0 = 32 * it + 16 * k2 + 8 * hh;
;                 const v4u ya = *(const v4u*)(yd + i0), ma = *(const v4u*)(EM + i0), aa = *(const v4u*)(ed + i0);
;                 yw[it][k2] = ya; mw[it][k2] = ma; aw[it][k2] = aa; }
;         asm volatile("" :: "v"(qf[0]), "v"(qf[1]), "v"(qf[2]), "v"(qf[3]), "v"(hf[0][0]), "v"(hf[0][1]), "v"(hf[0][2]), "v"(hf[0][3]), "v"(hf[1][0]), "v"(hf[1][1]), "v"(hf[1][2]), "v"(hf[1][3]));
;         asm volatile("" :: "v"(yw[0][0]), "v"(yw[0][1]), "v"(yw[1][0]), "v"(yw[1][1]), "v"(mw[0][0]), "v"(mw[0][1]), "v"(mw[1][0]), "v"(mw[1][1]), "v"(aw[0][0]), "v"(aw[0][1]), "v"(aw[1][0]), "v"(aw[1][1]));
; #pragma unroll
;         for (int it = 0; it < 2; ++it)
; #pragma unroll
;             for (int k2 = 0; k2 < 2; ++k2) {
;                 { const v4u v = yw[it][k2]; const v4u s = widen32((v2u){v.x, v.y}, (v2u){v.z, v.w}); yq[it][2 * k2] = (v2u){s.x, s.y}; yq[it][2 * k2 + 1] = (v2u){s.z, s.w}; }
;                 { const v4u v = mw[it][k2]; const v4u s = widen32((v2u){v.x, v.y}, (v2u){v.z, v.w}); em[it][2 * k2] = (v2u){s.x, s.y}; em[it][2 * k2 + 1] = (v2u){s.z, s.w}; }
.LBB0_164:
	s_ashr_i32 s1, s0, 6
	s_mul_hi_i32 s6, s1, 0x2aaaaaab
	s_lshr_b32 s7, s6, 31
	s_add_i32 s6, s6, s7
	s_mul_i32 s6, s6, 6
	s_sub_i32 s1, s1, s6
	s_mul_hi_i32 s6, s0, 0x2aaaaaab
	s_lshr_b32 s7, s6, 31
	s_ashr_i32 s6, s6, 6
	s_add_i32 s6, s6, s7
	s_mul_i32 s10, s6, 0x500000
	s_ashr_i32 s7, s6, 31
	s_lshl_b64 s[6:7], s[6:7], 12
	s_and_b32 s8, s3, 0xfc0
	s_or_b32 s6, s6, s8
	v_or_b32_e32 v2, s6, v64
	v_mov_b64_e32 v[0:1], s[82:83]
	v_mad_u64_u32 v[0:1], s[8:9], v2, s92, v[0:1]
	s_lshl_b32 s6, s1, 6
	v_mad_i32_i24 v1, s7, v236, v1
	s_ashr_i32 s7, s6, 31
	s_ashr_i32 s1, s0, 31
	v_lshl_add_u64 v[0:1], s[6:7], 1, v[0:1]
	s_lshl_b64 s[6:7], s[0:1], 13
	s_add_u32 s10, s6, s10
	s_addc_u32 s11, s7, 0
	v_lshl_add_u64 v[70:71], v[0:1], 0, v[80:81]
	v_lshl_add_u64 v[0:1], v[66:67], 0, s[10:11]
	global_load_dwordx4 v[72:75], v[70:71], off offset:2304
	global_load_dwordx4 v[76:79], v[0:1], off
	v_add_co_u32_e32 v2, vcc, s66, v0
	s_waitcnt vmcnt(6)
	v_lshl_add_u64 v[16:17], v[68:69], 0, s[6:7]
	v_addc_co_u32_e32 v3, vcc, 0, v1, vcc
	global_load_dwordx4 v[82:85], v[2:3], off
	global_load_dwordx4 v[86:89], v[70:71], off offset:2336
	global_load_dwordx4 v[90:93], v[0:1], off offset:1024
	global_load_dwordx4 v[94:97], v[2:3], off offset:1024
	global_load_dwordx4 v[98:101], v[70:71], off offset:2368
	global_load_dwordx4 v[102:105], v[0:1], off offset:2048
	global_load_dwordx4 v[106:109], v[2:3], off offset:2048
	global_load_dwordx4 v[110:113], v[70:71], off offset:2400
	global_load_dwordx4 v[114:117], v[0:1], off offset:3072
	global_load_dwordx4 v[118:121], v[2:3], off offset:3072
	s_nop 0
	global_load_dwordx4 v[0:3], v[70:71], off offset:3072
	global_load_dwordx4 v[56:59], v[16:17], off
	global_load_dwordx4 v[60:63], v[70:71], off offset:3840
	global_load_dwordx4 v[4:7], v[70:71], off offset:3104
	global_load_dwordx4 v[48:51], v[16:17], off offset:32
	global_load_dwordx4 v[52:55], v[70:71], off offset:3872
	global_load_dwordx4 v[8:11], v[70:71], off offset:3136
	global_load_dwordx4 v[40:43], v[16:17], off offset:64
	global_load_dwordx4 v[44:47], v[70:71], off offset:3904
	global_load_dwordx4 v[12:15], v[70:71], off offset:3168
	global_load_dwordx4 v[32:35], v[16:17], off offset:96
	global_load_dwordx4 v[36:39], v[70:71], off offset:3936
	s_mov_b32 s6, 0x3c800000
	s_add_i32 s5, s5, s93
	s_sub_i32 s0, s0, s2
	s_sub_i32 s3, s3, s4
	s_cmpk_lt_i32 s5, 0x300
	s_waitcnt vmcnt(12)
	s_waitcnt vmcnt(0)
	v_permlane32_swap_b32_e32 v0, v2
	v_permlane32_swap_b32_e32 v1, v3
	v_permlane32_swap_b32_e32 v4, v6
	v_permlane32_swap_b32_e32 v5, v7
	v_lshlrev_b32_e32 v16, 16, v0
	v_and_b32_e32 v17, 0xffff0000, v0
	v_lshlrev_b32_e32 v18, 16, v1
	v_and_b32_e32 v19, 0xffff0000, v1
	v_lshlrev_b32_e32 v20, 16, v2
	v_and_b32_e32 v21, 0xffff0000, v2
	v_lshlrev_b32_e32 v22, 16, v3
	v_and_b32_e32 v23, 0xffff0000, v3
	v_lshlrev_b32_e32 v24, 16, v4
	v_and_b32_e32 v25, 0xffff0000, v4
	v_lshlrev_b32_e32 v26, 16, v5
	v_and_b32_e32 v27, 0xffff0000, v5
	v_lshlrev_b32_e32 v28, 16, v6
	v_and_b32_e32 v29, 0xffff0000, v6
	v_lshlrev_b32_e32 v30, 16, v7
	v_and_b32_e32 v31, 0xffff0000, v7
	v_permlane32_swap_b32_e32 v8, v10
	s_nop 0
	v_mfma_f32_32x32x16_bf16 v[16:31], v[76:79], v[72:75], v[16:31]
	v_permlane32_swap_b32_e32 v9, v11
	v_permlane32_swap_b32_e32 v12, v14
	v_permlane32_swap_b32_e32 v13, v15
	v_lshlrev_b32_e32 v0, 16, v8
	v_mfma_f32_32x32x16_bf16 v[16:31], v[90:93], v[86:89], v[16:31]
	v_and_b32_e32 v1, 0xffff0000, v8
	v_lshlrev_b32_e32 v2, 16, v9
	v_and_b32_e32 v3, 0xffff0000, v9
	v_lshlrev_b32_e32 v4, 16, v10
	v_and_b32_e32 v5, 0xffff0000, v10
	v_lshlrev_b32_e32 v6, 16, v11
	v_and_b32_e32 v7, 0xffff0000, v11
	v_lshlrev_b32_e32 v8, 16, v12
	v_and_b32_e32 v9, 0xffff0000, v12
	v_lshlrev_b32_e32 v10, 16, v13
	v_and_b32_e32 v11, 0xffff0000, v13
	v_lshlrev_b32_e32 v12, 16, v14
	v_and_b32_e32 v13, 0xffff0000, v14
	v_lshlrev_b32_e32 v14, 16, v15
	v_and_b32_e32 v15, 0xffff0000, v15
	v_mfma_f32_32x32x16_bf16 v[16:31], v[102:105], v[98:101], v[16:31]
	v_mov_b32_e32 v125, v34
	v_mov_b32_e32 v123, v46
	v_mov_b32_e32 v124, v47
	v_mov_b32_e32 v65, v42
	v_mov_b32_e32 v122, v43
	v_mov_b32_e32 v127, v38
	v_mov_b32_e32 v128, v39
	v_mfma_f32_32x32x16_bf16 v[0:15], v[82:85], v[72:75], v[0:15]
	v_mov_b32_e32 v126, v35
	v_permlane32_swap_b32_e32 v56, v58
	v_permlane32_swap_b32_e32 v60, v62
	v_permlane32_swap_b32_e32 v57, v59
	v_mfma_f32_32x32x16_bf16 v[16:31], v[114:117], v[110:113], v[16:31]
	v_permlane32_swap_b32_e32 v61, v63
	v_permlane32_swap_b32_e32 v48, v50
	v_permlane32_swap_b32_e32 v52, v54
	v_permlane32_swap_b32_e32 v49, v51
	v_mfma_f32_32x32x16_bf16 v[0:15], v[94:97], v[86:89], v[0:15]
	s_nop 6
	v_add_f32_e32 v34, 0, v16
	v_mul_f32_e32 v72, v17, v17
	v_add_f32_e32 v34, v17, v34
	v_fmac_f32_e32 v72, v16, v16
	v_add_f32_e32 v34, v18, v34
	v_fmac_f32_e32 v72, v18, v18
	v_add_f32_e32 v34, v19, v34
	v_mfma_f32_32x32x16_bf16 v[0:15], v[106:109], v[98:101], v[0:15]
	v_fmac_f32_e32 v72, v19, v19
	v_add_f32_e32 v34, v20, v34
	v_fmac_f32_e32 v72, v20, v20
	v_add_f32_e32 v34, v21, v34
	v_fmac_f32_e32 v72, v21, v21
	v_add_f32_e32 v34, v22, v34
	v_fmac_f32_e32 v72, v22, v22
	v_add_f32_e32 v34, v23, v34
	v_fmac_f32_e32 v72, v23, v23
	v_mfma_f32_32x32x16_bf16 v[0:15], v[118:121], v[110:113], v[0:15]
	v_add_f32_e32 v34, v24, v34
	v_fmac_f32_e32 v72, v24, v24
	v_add_f32_e32 v34, v25, v34
	v_fmac_f32_e32 v72, v25, v25
	v_add_f32_e32 v34, v26, v34
	v_fmac_f32_e32 v72, v26, v26
	v_add_f32_e32 v34, v27, v34
	v_fmac_f32_e32 v72, v27, v27
	v_add_f32_e32 v34, v28, v34
	v_fmac_f32_e32 v72, v28, v28
	v_add_f32_e32 v34, v29, v34
	v_fmac_f32_e32 v72, v29, v29
	v_add_f32_e32 v34, v30, v34
	v_fmac_f32_e32 v72, v30, v30
; __device__ __forceinline__ unsigned cvtpk(float lo, float hi) { f32x2_t v = {lo, hi}; bf16x2_t b = __builtin_convertvector(v, bf16x2_t); return __builtin_bit_cast(unsigned, b); }
; __device__ __forceinline__ float bflo(unsigned w) { return __uint_as_float(w << 16); }
; __device__ __forceinline__ float bfhi(unsigned w) { return __uint_as_float(w & 0xffff0000u); }
; __device__ __forceinline__ float xsum32(float v) { auto r = __builtin_amdgcn_permlane32_swap(__float_as_uint(v), __float_as_uint(v), false, false); return __uint_as_float(r[0]) + __uint_as_float(r[1]); }
; __device__ __forceinline__ void rwkv_p3(const KA& A, const Ctx& F) {
;     ...
;         s1 = xsum32(s1); s2 = xsum32(s2);
;         const float mu = s1 * (1.0f / 64.0f); const float var = fmaxf(s2 * (1.0f / 64.0f) - mu * mu, 0.f); const float rs = __builtin_amdgcn_rsqf(var + GN_EPS);
;         bf16* od = PS + (row0 + t) * PSW + 384 + h * 64;
; #pragma unroll
;         for (int it = 0; it < 2; ++it)
; #pragma unroll
;             for (int k2 = 0; k2 < 2; ++k2) { v2u wq[2];
; #pragma unroll
;                 for (int e = 0; e < 2; ++e) { const int g4 = 2 * k2 + e; const v2u emv = em[it][g4], eav = ea[it][g4];
;                     wq[e].x = cvtpk((y[it][4 * g4] - mu) * rs * bflo(emv.x) + bflo(eav.x), (y[it][4 * g4 + 1] - mu) * rs * bfhi(emv.x) + bfhi(eav.x));
;                     wq[e].y = cvtpk((y[it][4 * g4 + 2] - mu) * rs * bflo(emv.y) + bflo(eav.y), (y[it][4 * g4 + 3] - mu) * rs * bfhi(emv.y) + bfhi(eav.y)); }
;                 const v4u wv = widen32(wq[0], wq[1]);
;                 if (!(F.dry && (DRY_SEL & 4))) *(v4u*)(od + 32 * it + 16 * k2 + 8 * hh) = wv; }
	v_add_f32_e32 v34, v31, v34
	v_fmac_f32_e32 v72, v31, v31
	v_add_f32_e32 v34, v0, v34
	v_fmac_f32_e32 v72, v0, v0
	v_add_f32_e32 v34, v1, v34
	v_fmac_f32_e32 v72, v1, v1
	v_add_f32_e32 v34, v2, v34
	v_fmac_f32_e32 v72, v2, v2
	v_add_f32_e32 v34, v3, v34
	v_fmac_f32_e32 v72, v3, v3
	v_add_f32_e32 v34, v4, v34
	v_fmac_f32_e32 v72, v4, v4
	v_add_f32_e32 v34, v5, v34
	v_fmac_f32_e32 v72, v5, v5
	v_add_f32_e32 v34, v6, v34
	v_fmac_f32_e32 v72, v6, v6
	v_add_f32_e32 v34, v7, v34
	v_fmac_f32_e32 v72, v7, v7
	v_pk_mul_f32 v[46:47], v[8:9], v[8:9]
	v_add_f32_e32 v34, v8, v34
	v_add_f32_e32 v46, v46, v72
	v_add_f32_e32 v73, v9, v34
	v_pk_mul_f32 v[42:43], v[10:11], v[10:11]
	v_add_f32_e32 v46, v47, v46
	v_add_f32_e32 v47, v10, v73
	v_add_f32_e32 v42, v42, v46
	v_pk_mul_f32 v[38:39], v[12:13], v[12:13]
	v_add_f32_e32 v47, v11, v47
	v_add_f32_e32 v42, v43, v42
	v_add_f32_e32 v43, v12, v47
	v_add_f32_e32 v38, v38, v42
	v_pk_mul_f32 v[34:35], v[14:15], v[14:15]
	v_add_f32_e32 v43, v13, v43
	v_add_f32_e32 v38, v39, v38
	v_add_f32_e32 v39, v14, v43
	v_add_f32_e32 v34, v34, v38
	v_add_f32_e32 v39, v15, v39
	v_add_f32_e32 v38, v35, v34
	v_mov_b32_e32 v35, v39
	v_mov_b32_e32 v34, v38
	s_nop 0
	v_permlane32_swap_b32_e32 v39, v35
	v_permlane32_swap_b32_e32 v38, v34
	v_pk_add_f32 v[34:35], v[38:39], v[34:35]
	v_lshlrev_b32_e32 v42, 16, v56
	v_pk_mul_f32 v[34:35], v[34:35], s[6:7] op_sel_hi:[1,0]
	v_lshlrev_b32_e32 v46, 16, v60
	v_fma_f32 v38, -v35, v35, v34
	v_max_f32_e32 v38, 0, v38
	v_add_f32_e32 v38, 0x3a27c5ac, v38
	v_rsq_f32_e32 v38, v38
	v_pk_add_f32 v[16:17], v[16:17], v[34:35] op_sel:[0,1] neg_lo:[0,1] neg_hi:[0,1]
	v_and_b32_e32 v43, 0xffff0000, v56
	v_and_b32_e32 v47, 0xffff0000, v60
	v_pk_mul_f32 v[16:17], v[16:17], v[38:39] op_sel_hi:[1,0]
	v_pk_add_f32 v[18:19], v[18:19], v[34:35] op_sel:[0,1] neg_lo:[0,1] neg_hi:[0,1]
	v_pk_fma_f32 v[16:17], v[16:17], v[42:43], v[46:47]
	v_lshlrev_b32_e32 v42, 16, v57
	v_lshlrev_b32_e32 v46, 16, v61
	v_and_b32_e32 v43, 0xffff0000, v57
	v_and_b32_e32 v47, 0xffff0000, v61
	v_pk_mul_f32 v[18:19], v[18:19], v[38:39] op_sel_hi:[1,0]
	v_pk_add_f32 v[20:21], v[20:21], v[34:35] op_sel:[0,1] neg_lo:[0,1] neg_hi:[0,1]
	v_pk_fma_f32 v[18:19], v[18:19], v[42:43], v[46:47]
	v_cvt_pk_bf16_f32 v16, v16, v17
	v_cvt_pk_bf16_f32 v17, v18, v19
	v_lshlrev_b32_e32 v18, 16, v58
	v_lshlrev_b32_e32 v42, 16, v62
	v_and_b32_e32 v19, 0xffff0000, v58
	v_and_b32_e32 v43, 0xffff0000, v62
	v_pk_mul_f32 v[20:21], v[20:21], v[38:39] op_sel_hi:[1,0]
	v_pk_add_f32 v[22:23], v[22:23], v[34:35] op_sel:[0,1] neg_lo:[0,1] neg_hi:[0,1]
	v_pk_fma_f32 v[18:19], v[20:21], v[18:19], v[42:43]
	v_lshlrev_b32_e32 v20, 16, v59
	v_lshlrev_b32_e32 v42, 16, v63
	v_and_b32_e32 v21, 0xffff0000, v59
	v_and_b32_e32 v43, 0xffff0000, v63
	v_pk_mul_f32 v[22:23], v[22:23], v[38:39] op_sel_hi:[1,0]
	v_cvt_pk_bf16_f32 v18, v18, v19
	v_pk_fma_f32 v[20:21], v[22:23], v[20:21], v[42:43]
	s_nop 0
	v_permlane32_swap_b32_e32 v16, v18
	v_cvt_pk_bf16_f32 v19, v20, v21
	s_nop 1
	v_permlane32_swap_b32_e32 v17, v19
	v_pk_add_f32 v[20:21], v[24:25], v[34:35] op_sel:[0,1] neg_lo:[0,1] neg_hi:[0,1]
	v_permlane32_swap_b32_e32 v53, v55
	global_store_dwordx4 v[70:71], v[16:19], off offset:768
	v_pk_mul_f32 v[20:21], v[20:21], v[38:39] op_sel_hi:[1,0]
	v_pk_add_f32 v[22:23], v[26:27], v[34:35] op_sel:[0,1] neg_lo:[0,1] neg_hi:[0,1]
	v_lshlrev_b32_e32 v16, 16, v48
	v_lshlrev_b32_e32 v18, 16, v52
	v_and_b32_e32 v17, 0xffff0000, v48
	v_and_b32_e32 v19, 0xffff0000, v52
	v_pk_fma_f32 v[16:17], v[20:21], v[16:17], v[18:19]
	v_lshlrev_b32_e32 v18, 16, v49
	v_lshlrev_b32_e32 v20, 16, v53
	v_and_b32_e32 v19, 0xffff0000, v49
	v_and_b32_e32 v21, 0xffff0000, v53
	v_pk_mul_f32 v[22:23], v[22:23], v[38:39] op_sel_hi:[1,0]
	v_cvt_pk_bf16_f32 v16, v16, v17
	v_pk_fma_f32 v[18:19], v[22:23], v[18:19], v[20:21]
	v_pk_add_f32 v[22:23], v[28:29], v[34:35] op_sel:[0,1] neg_lo:[0,1] neg_hi:[0,1]
	v_cvt_pk_bf16_f32 v17, v18, v19
	v_lshlrev_b32_e32 v18, 16, v50
	v_lshlrev_b32_e32 v20, 16, v54
	v_and_b32_e32 v19, 0xffff0000, v50
; __device__ __forceinline__ unsigned cvtpk(float lo, float hi) { f32x2_t v = {lo, hi}; bf16x2_t b = __builtin_convertvector(v, bf16x2_t); return __builtin_bit_cast(unsigned, b); }
; __device__ __forceinline__ float bflo(unsigned w) { return __uint_as_float(w << 16); }
; __device__ __forceinline__ float bfhi(unsigned w) { return __uint_as_float(w & 0xffff0000u); }
; __device__ __forceinline__ void rwkv_p3(const KA& A, const Ctx& F) {
;     ...
;         bf16* od = PS + (row0 + t) * PSW + 384 + h * 64;
; #pragma unroll
;         for (int it = 0; it < 2; ++it)
; #pragma unroll
;             for (int k2 = 0; k2 < 2; ++k2) { v2u wq[2];
; #pragma unroll
;                 for (int e = 0; e < 2; ++e) { const int g4 = 2 * k2 + e; const v2u emv = em[it][g4], eav = ea[it][g4];
;                     wq[e].x = cvtpk((y[it][4 * g4] - mu) * rs * bflo(emv.x) + bflo(eav.x), (y[it][4 * g4 + 1] - mu) * rs * bfhi(emv.x) + bfhi(eav.x));
;                     wq[e].y = cvtpk((y[it][4 * g4 + 2] - mu) * rs * bflo(emv.y) + bflo(eav.y), (y[it][4 * g4 + 3] - mu) * rs * bfhi(emv.y) + bfhi(eav.y)); }
;                 const v4u wv = widen32(wq[0], wq[1]);
;                 if (!(F.dry && (DRY_SEL & 4))) *(v4u*)(od + 32 * it + 16 * k2 + 8 * hh) = wv; }
;     }
	v_and_b32_e32 v21, 0xffff0000, v54
	v_pk_mul_f32 v[22:23], v[22:23], v[38:39] op_sel_hi:[1,0]
	v_pk_add_f32 v[24:25], v[30:31], v[34:35] op_sel:[0,1] neg_lo:[0,1] neg_hi:[0,1]
	v_pk_fma_f32 v[18:19], v[22:23], v[18:19], v[20:21]
	v_lshlrev_b32_e32 v20, 16, v51
	v_lshlrev_b32_e32 v22, 16, v55
	v_and_b32_e32 v21, 0xffff0000, v51
	v_and_b32_e32 v23, 0xffff0000, v55
	v_pk_mul_f32 v[24:25], v[24:25], v[38:39] op_sel_hi:[1,0]
	v_cvt_pk_bf16_f32 v18, v18, v19
	v_pk_fma_f32 v[20:21], v[24:25], v[20:21], v[22:23]
	v_permlane32_swap_b32_e32 v40, v65
	v_cvt_pk_bf16_f32 v19, v20, v21
	v_permlane32_swap_b32_e32 v44, v123
	v_permlane32_swap_b32_e32 v16, v18
	v_permlane32_swap_b32_e32 v17, v19
	v_pk_add_f32 v[0:1], v[0:1], v[34:35] op_sel:[0,1] neg_lo:[0,1] neg_hi:[0,1]
	v_permlane32_swap_b32_e32 v41, v122
	v_permlane32_swap_b32_e32 v45, v124
	global_store_dwordx4 v[70:71], v[16:19], off offset:800
	v_pk_mul_f32 v[0:1], v[0:1], v[38:39] op_sel_hi:[1,0]
	v_pk_add_f32 v[2:3], v[2:3], v[34:35] op_sel:[0,1] neg_lo:[0,1] neg_hi:[0,1]
	v_lshlrev_b32_e32 v16, 16, v40
	v_lshlrev_b32_e32 v18, 16, v44
	v_and_b32_e32 v17, 0xffff0000, v40
	v_and_b32_e32 v19, 0xffff0000, v44
	v_pk_fma_f32 v[0:1], v[0:1], v[16:17], v[18:19]
	v_lshlrev_b32_e32 v16, 16, v41
	v_lshlrev_b32_e32 v18, 16, v45
	v_and_b32_e32 v17, 0xffff0000, v41
	v_and_b32_e32 v19, 0xffff0000, v45
	v_pk_mul_f32 v[2:3], v[2:3], v[38:39] op_sel_hi:[1,0]
	v_pk_add_f32 v[4:5], v[4:5], v[34:35] op_sel:[0,1] neg_lo:[0,1] neg_hi:[0,1]
	v_pk_fma_f32 v[2:3], v[2:3], v[16:17], v[18:19]
	v_cvt_pk_bf16_f32 v0, v0, v1
	v_cvt_pk_bf16_f32 v1, v2, v3
	v_lshlrev_b32_e32 v2, 16, v65
	v_lshlrev_b32_e32 v16, 16, v123
	v_and_b32_e32 v3, 0xffff0000, v65
	v_and_b32_e32 v17, 0xffff0000, v123
	v_pk_mul_f32 v[4:5], v[4:5], v[38:39] op_sel_hi:[1,0]
	v_pk_add_f32 v[6:7], v[6:7], v[34:35] op_sel:[0,1] neg_lo:[0,1] neg_hi:[0,1]
	v_pk_fma_f32 v[2:3], v[4:5], v[2:3], v[16:17]
	v_lshlrev_b32_e32 v4, 16, v122
	v_lshlrev_b32_e32 v16, 16, v124
	v_and_b32_e32 v5, 0xffff0000, v122
	v_and_b32_e32 v17, 0xffff0000, v124
	v_pk_mul_f32 v[6:7], v[6:7], v[38:39] op_sel_hi:[1,0]
	v_cvt_pk_bf16_f32 v2, v2, v3
	v_pk_fma_f32 v[4:5], v[6:7], v[4:5], v[16:17]
	v_permlane32_swap_b32_e32 v32, v125
	v_cvt_pk_bf16_f32 v3, v4, v5
	v_permlane32_swap_b32_e32 v36, v127
	v_permlane32_swap_b32_e32 v0, v2
	v_permlane32_swap_b32_e32 v1, v3
	v_pk_add_f32 v[4:5], v[8:9], v[34:35] op_sel:[0,1] neg_lo:[0,1] neg_hi:[0,1]
	v_permlane32_swap_b32_e32 v33, v126
	v_permlane32_swap_b32_e32 v37, v128
	global_store_dwordx4 v[70:71], v[0:3], off offset:832
	v_pk_mul_f32 v[4:5], v[4:5], v[38:39] op_sel_hi:[1,0]
	v_pk_add_f32 v[6:7], v[10:11], v[34:35] op_sel:[0,1] neg_lo:[0,1] neg_hi:[0,1]
	v_lshlrev_b32_e32 v0, 16, v32
	v_lshlrev_b32_e32 v2, 16, v36
	v_and_b32_e32 v1, 0xffff0000, v32
	v_and_b32_e32 v3, 0xffff0000, v36
	v_pk_fma_f32 v[0:1], v[4:5], v[0:1], v[2:3]
	v_lshlrev_b32_e32 v2, 16, v33
	v_lshlrev_b32_e32 v4, 16, v37
	v_and_b32_e32 v3, 0xffff0000, v33
	v_and_b32_e32 v5, 0xffff0000, v37
	v_pk_mul_f32 v[6:7], v[6:7], v[38:39] op_sel_hi:[1,0]
	v_cvt_pk_bf16_f32 v0, v0, v1
	v_pk_fma_f32 v[2:3], v[6:7], v[2:3], v[4:5]
	v_pk_add_f32 v[6:7], v[12:13], v[34:35] op_sel:[0,1] neg_lo:[0,1] neg_hi:[0,1]
	v_cvt_pk_bf16_f32 v1, v2, v3
	v_lshlrev_b32_e32 v2, 16, v125
	v_lshlrev_b32_e32 v4, 16, v127
	v_and_b32_e32 v3, 0xffff0000, v125
	v_and_b32_e32 v5, 0xffff0000, v127
	v_pk_mul_f32 v[6:7], v[6:7], v[38:39] op_sel_hi:[1,0]
	v_pk_add_f32 v[8:9], v[14:15], v[34:35] op_sel:[0,1] neg_lo:[0,1] neg_hi:[0,1]
	v_pk_fma_f32 v[2:3], v[6:7], v[2:3], v[4:5]
	v_lshlrev_b32_e32 v4, 16, v126
	v_lshlrev_b32_e32 v6, 16, v128
	v_and_b32_e32 v5, 0xffff0000, v126
	v_and_b32_e32 v7, 0xffff0000, v128
	v_pk_mul_f32 v[8:9], v[8:9], v[38:39] op_sel_hi:[1,0]
	v_cvt_pk_bf16_f32 v2, v2, v3
	v_pk_fma_f32 v[4:5], v[8:9], v[4:5], v[6:7]
	s_nop 0
	v_permlane32_swap_b32_e32 v0, v2
	v_cvt_pk_bf16_f32 v3, v4, v5
	s_nop 1
	v_permlane32_swap_b32_e32 v1, v3
	global_store_dwordx4 v[70:71], v[0:3], off offset:864
	s_cbranch_scc1 .LBB0_164

;     __device__ __forceinline__ unsigned char* ws() const { return *(const __attribute__((address_space(4))) ucptr_t*)(p + 264); }
; #define LAUNDER(Fx) Ctx Fx = F; asm volatile("" : "+v"(Fx.tid)); Fx.lane = Fx.tid & 63; Fx.wave = __builtin_amdgcn_readfirstlane(Fx.tid >> 6)
; __device__ __forceinline__ void ssm_v2(const KA& A, const Ctx& F, int l, int b, int g) {
;     bf16* PS = (bf16*)(F.ws + WS_PS);
;     float* ZF = (float*)F.lds;
;     const unsigned char* base = F.ws + WS_SSM + (size_t)(l * 16 + g) * SSG_BYTES;
;     const bf16* TM = (const bf16*)(base + SSG_TM); const bf16* GM = (const bf16*)(base + SSG_GM); const bf16* HM = (const bf16*)(base + SSG_HM); const float* lam = (const float*)(base + SSG_LAM);
;     const int lane = F.lane, w = F.wave, r32 = lane & 31, hh = lane >> 5;
;     const size_t tok0 = (size_t)b * SEQ + 512 * w;
;     bf16x8_t uf[16];
;     { const bf16* up = PS + (tok0 + 16 * r32) * PSW + C_SSM + 16 * g + 8 * hh;
; #pragma unroll
;       for (int s = 0; s < 16; ++s) uf[s] = *(const bf16x8_t*)(up + (size_t)s * PSW); }
; __device__ __forceinline__ void run_phase(const KA& A, const Ctx& F, int ph) {
;     ...
;         { LAUNDER(F1);
;           if (F1.bid < 48) { if (p3m & 1) rwkv_scan(A, F1, l, F1.bid / 6, F1.bid % 6); }
;           else if (F1.bid < 176) { if (p3m & 2) { const int it = F1.bid - 48; ssm_v2(A, F1, l, it / 16, it % 16); } } }
.LBB0_169:
	s_and_b64 vcc, exec, s[2:3]
	s_cbranch_vccz .LBB0_216
	s_cmp_gt_i32 s25, 1
	s_mov_b64 s[0:1], -1
	s_cbranch_scc0 .LBB0_214
	v_mov_b32_e32 v130, v242
	v_writelane_b32 v255, s4, 40
	v_readfirstlane_b32 s2, v130
	s_ashr_i32 s6, s2, 6
	v_writelane_b32 v255, s5, 41
	v_and_b32_e32 v114, 63, v130
	s_cmp_gt_i32 s80, 47
	s_mov_b64 s[34:35], 0x2000
	s_cbranch_scc0 .LBB0_182
	s_cmpk_gt_u32 s80, 0xaf
	s_cbranch_scc1 .LBB0_181
	s_and_b32 s0, s80, 7
	s_lshl_b32 s0, s0, 12
	s_lshl_b32 s1, s6, 9
	s_lshl_b32 s3, s79, 4
	s_lshr_b32 s4, s80, 3
	s_add_i32 s4, s4, -6
	s_ashr_i32 s5, s1, 31
	v_and_b32_e32 v85, 31, v130
	s_add_u32 s8, s1, s0
	v_lshl_or_b32 v2, v85, 4, s8
	v_mov_b64_e32 v[0:1], s[82:83]
	s_addc_u32 s7, s5, 0
	v_mad_u64_u32 v[0:1], s[0:1], v2, s92, v[0:1]
	v_lshrrev_b32_e32 v84, 5, v114
	v_mad_i32_i24 v1, s7, v236, v1
	s_lshl_b32 s0, s4, 5
	s_mov_b32 s1, s24
	v_lshl_add_u64 v[0:1], v[0:1], 0, s[0:1]
	v_lshlrev_b32_e32 v80, 4, v84
	v_lshl_add_u64 v[0:1], v[0:1], 0, v[80:81]
	v_add_co_u32_e32 v2, vcc, s66, v0
	s_movk_i32 s0, 0x2000
	s_nop 0
	v_addc_co_u32_e32 v3, vcc, 0, v1, vcc
	v_add_co_u32_e32 v4, vcc, s0, v0
	s_movk_i32 s0, 0x5000
	s_nop 0
	v_addc_co_u32_e32 v5, vcc, 0, v1, vcc
	global_load_dwordx4 v[20:23], v[2:3], off offset:1024
	global_load_dwordx4 v[24:27], v[4:5], off offset:2560
	v_add_co_u32_e32 v2, vcc, s73, v0
	s_lshl_b32 s9, s4, 4
	s_nop 0
	v_addc_co_u32_e32 v3, vcc, 0, v1, vcc
	v_add_co_u32_e32 v4, vcc, s0, v0
	s_movk_i32 s0, 0x6000
	s_nop 0
	v_addc_co_u32_e32 v5, vcc, 0, v1, vcc
	global_load_dwordx4 v[28:31], v[2:3], off
	global_load_dwordx4 v[16:19], v[4:5], off offset:1536
	v_add_co_u32_e32 v2, vcc, s0, v0
	s_mov_b32 s0, 0x8000
	s_nop 0
	v_addc_co_u32_e32 v3, vcc, 0, v1, vcc
	v_add_co_u32_e32 v4, vcc, s0, v0
	s_mov_b32 s0, 0x9000
	s_nop 0
	v_addc_co_u32_e32 v5, vcc, 0, v1, vcc
	global_load_dwordx4 v[32:35], v[2:3], off offset:3072
	global_load_dwordx4 v[36:39], v[4:5], off offset:512
	v_add_co_u32_e32 v2, vcc, s0, v0
	s_mov_b32 s0, 0xa000
	s_nop 0
	v_addc_co_u32_e32 v3, vcc, 0, v1, vcc
	v_add_co_u32_e32 v4, vcc, s0, v0
	s_mov_b32 s0, 0xc000
	s_nop 0
	v_addc_co_u32_e32 v5, vcc, 0, v1, vcc
	global_load_dwordx4 v[52:55], v[2:3], off offset:2048
	global_load_dwordx4 v[48:51], v[4:5], off offset:3584
	v_add_co_u32_e32 v2, vcc, s0, v0
	s_mov_b32 s0, 0xd000
	s_nop 0
	v_addc_co_u32_e32 v3, vcc, 0, v1, vcc
	v_add_co_u32_e32 v4, vcc, s0, v0
	s_mov_b32 s0, 0xf000
	s_nop 0
	v_addc_co_u32_e32 v5, vcc, 0, v1, vcc
	global_load_dwordx4 v[40:43], v[2:3], off offset:1024
	global_load_dwordx4 v[44:47], v[4:5], off offset:2560
	v_add_co_u32_e32 v2, vcc, s0, v0
	s_mov_b32 s0, 0x10000
	s_nop 0
	v_addc_co_u32_e32 v3, vcc, 0, v1, vcc
	v_add_co_u32_e32 v4, vcc, s0, v0
	s_mov_b32 s0, 0x11000
	s_nop 0
	v_addc_co_u32_e32 v5, vcc, 0, v1, vcc
	global_load_dwordx4 v[56:59], v[2:3], off
	global_load_dwordx4 v[60:63], v[4:5], off offset:1536
	v_add_co_u32_e32 v2, vcc, s0, v0
	s_mov_b32 s0, 0x13000
	s_nop 0
	v_addc_co_u32_e32 v3, vcc, 0, v1, vcc
	v_add_co_u32_e32 v4, vcc, s0, v0
	s_mov_b32 s0, 0x14000
	s_nop 0
	v_addc_co_u32_e32 v5, vcc, 0, v1, vcc
	global_load_dwordx4 v[64:67], v[2:3], off offset:3072
	global_load_dwordx4 v[68:71], v[4:5], off offset:512
	v_add_co_u32_e32 v2, vcc, s0, v0
	s_mov_b32 s0, 0x15000
	s_nop 0
	v_addc_co_u32_e32 v3, vcc, 0, v1, vcc
	v_add_co_u32_e32 v0, vcc, s0, v0
	s_mul_i32 s0, s6, 0x4200
	s_nop 0
	v_addc_co_u32_e32 v1, vcc, 0, v1, vcc
	global_load_dwordx4 v[76:79], v[2:3], off offset:2048
	global_load_dwordx4 v[72:75], v[0:1], off offset:3584
	s_or_b32 s4, s3, s4
	v_readlane_b32 s12, v253, 60
	v_mov_b32_e32 v0, s0
	s_movk_i32 s0, 0x840
	s_mul_hi_i32 s3, s4, 0x40400
	s_mul_i32 s4, s4, 0x40400
	v_readlane_b32 s14, v253, 62
	v_mad_u32_u24 v0, v84, s0, v0
	v_readlane_b32 s15, v253, 63
	s_add_u32 s0, s14, s4
	v_lshlrev_b32_e32 v1, 2, v85
	v_lshlrev_b32_e32 v80, 4, v114
	s_addc_u32 s1, s15, s3
	v_lshlrev_b32_e32 v86, 3, v84
	v_add3_u32 v87, v0, v1, 0
	v_lshl_add_u64 v[82:83], s[0:1], 0, v[80:81]
	s_mov_b64 s[0:1], 0
	v_readlane_b32 s13, v253, 61

; __device__ __forceinline__ unsigned cvtpk(float lo, float hi) { f32x2_t v = {lo, hi}; bf16x2_t b = __builtin_convertvector(v, bf16x2_t); return __builtin_bit_cast(unsigned, b); }
; __device__ __forceinline__ float bflo(unsigned w) { return __uint_as_float(w << 16); }
; __device__ __forceinline__ float bfhi(unsigned w) { return __uint_as_float(w & 0xffff0000u); }
; __device__ __forceinline__ void rwkv_scan(const KA& A, const Ctx& F, int l, int b, int h) {
;     ...
;     const size_t item0 = (size_t)(b * 6 + h) * 64;
;     bf16* __restrict__ HS = (bf16*)(F.ws + WS_RHS) + item0 * 4096;
;     const bf16* MC = (const bf16*)(F.ws + WS_RMC) + item0 * 4096; const bf16* NT = (const bf16*)(F.ws + WS_RNT) + item0 * 4096; const float* GL = (const float*)(F.ws + WS_RGL) + item0 * 64;
;     ...
;         const int ta = (w >> 1) & 1, tb2 = w & 1;
;         f32x16 Hacc = {};
;         SCAN_BAR();
; #pragma unroll 2
;         for (int j = 0; j < 64; ++j) {
;             const unsigned char* HBc = L + (j & 1) * 9216; unsigned char* HBn = L + ((j + 1) & 1) * 9216;
;             const unsigned char* sb = L + SC_RING + (j % SC_NS) * SC_SLOT;
;             if (wr) {
; #pragma unroll
;                 for (int g4 = 0; g4 < 4; ++g4) { v2u wv; wv.x = cvtpk(Hacc[4 * g4], Hacc[4 * g4 + 1]); wv.y = cvtpk(Hacc[4 * g4 + 2], Hacc[4 * g4 + 3]); *(v2u*)(HS + (size_t)j * 4096 + (((tb2 * 4 + 2 * ta + (g4 >> 1)) * 64 + (g4 & 1) * 32 + r32) << 3) + 4 * hh) = wv; } }
;             bf16x8_t mf[4];
; #pragma unroll
;             for (int s = 0; s < 4; ++s) mf[s] = *(const bf16x8_t*)(sb + ((32 * ta + r32) * 64 + 16 * s + 8 * hh) * 2);
; #pragma unroll
;             for (int g4 = 0; g4 < 4; ++g4) { const int c0 = 32 * ta + 8 * g4 + 4 * hh; const f32x4 gl = *(const f32x4*)(sb + 16384 + c0 * 4); const v2u nv = *(const v2u*)(sb + 8192 + ((32 * tb2 + r32) * 64 + c0) * 2);
;                 Hacc[4 * g4 + 0] = Hacc[4 * g4 + 0] * gl[0] + bflo(nv.x); Hacc[4 * g4 + 1] = Hacc[4 * g4 + 1] * gl[1] + bfhi(nv.x); Hacc[4 * g4 + 2] = Hacc[4 * g4 + 2] * gl[2] + bflo(nv.y); Hacc[4 * g4 + 3] = Hacc[4 * g4 + 3] * gl[3] + bfhi(nv.y); }
; #pragma unroll
;             for (int s = 0; s < 4; ++s) Hacc = __builtin_amdgcn_mfma_f32_32x32x16_bf16(mf[s], ldfrag(HBc, 32 * tb2 + r32, s, hh), Hacc, 0, 0, 0);
;             st_tileT(HBn, 32 * tb2 + r32, 32 * ta, Hacc, hh);
;             SCAN_BAR();
;         }
.LBB0_186:
	s_or_b64 exec, exec, s[0:1]
	s_ashr_i32 s81, s80, 31
	s_and_b32 s40, s80, 7
	s_mul_i32 s42, s40, 0x500000
	s_add_i32 s42, s42, 0x4400000
	s_add_i32 s43, s42, 0x2000
	s_mulk_i32 s40, 6
	s_lshr_b32 s41, s80, 3
	s_add_i32 s40, s40, s41
	s_mov_b32 s41, 0
	s_cmp_lt_i32 s6, 4
	s_mov_b64 s[0:1], -1
	s_cbranch_scc0 .LBB0_190
	v_lshrrev_b32_e32 v1, 5, v114
	v_and_b32_e32 v0, 31, v130
	s_bfe_u32 s0, s6, 0x10001
	s_and_b32 s3, s6, 3
	v_lshlrev_b32_e32 v2, 2, v1
	s_and_b32 s1, s6, 1
	s_brev_b32 s4, s3
	s_lshl_b32 s3, s0, 12
	v_lshl_or_b32 v2, s0, 5, v2
	v_lshlrev_b32_e32 v3, 6, v0
	s_lshl_b32 s0, s0, 6
	v_lshl_or_b32 v3, s1, 11, v3
	s_add_i32 s0, s0, 0
	s_waitcnt vmcnt(9)
	v_lshlrev_b32_e32 v37, 4, v1
	v_lshl_add_u32 v6, v1, 3, s0
	v_or_b32_e32 v1, v2, v3
	v_lshlrev_b32_e32 v39, 1, v1
	v_or_b32_e32 v1, 8, v2
	v_lshlrev_b32_e32 v40, 2, v1
	v_or_b32_e32 v1, v1, v3
	v_lshlrev_b32_e32 v41, 1, v1
	v_or_b32_e32 v1, 16, v2
	v_lshlrev_b32_e32 v42, 2, v1
	v_or_b32_e32 v1, v1, v3
	v_lshlrev_b32_e32 v43, 1, v1
	v_or_b32_e32 v1, 24, v2
	v_lshlrev_b32_e32 v44, 2, v1
	v_or_b32_e32 v1, v1, v3
	v_lshlrev_b32_e32 v45, 1, v1
	v_and_b32_e32 v1, 32, v130
	s_lshr_b32 s4, s4, 19
	v_lshlrev_b32_e32 v36, 7, v0
	v_lshl_or_b32 v4, s1, 5, v0
	s_lshl_b64 s[0:1], s[40:41], 19
	v_lshrrev_b32_e32 v1, 2, v1
	v_lshl_or_b32 v0, v0, 4, s4
	v_readlane_b32 s8, v253, 60
	s_waitcnt lgkmcnt(0)
	s_barrier
	v_or3_b32 v0, s0, v1, v0
	v_mov_b32_e32 v1, s1
	v_readlane_b32 s10, v253, 62
	v_readlane_b32 s11, v253, 63
	v_mul_u32_u24_e32 v5, 0x90, v4
	v_lshlrev_b32_e32 v38, 2, v2
	v_mad_u32_u24 v2, v4, s56, 0
	s_waitcnt vmcnt(8)
	v_lshl_add_u64 v[32:33], s[10:11], 0, v[0:1]
	v_mov_b32_e32 v0, 0
	s_mov_b32 s2, 1
	s_mov_b64 s[0:1], 0
	v_add_u32_e32 v46, v2, v37
	v_add_u32_e32 v47, v6, v5
	v_mov_b32_e32 v1, v0
	v_mov_b32_e32 v2, v0
	v_mov_b32_e32 v3, v0
	v_mov_b32_e32 v4, v0
	v_mov_b32_e32 v5, v0
	v_mov_b32_e32 v6, v0
	v_mov_b32_e32 v7, v0
	v_mov_b32_e32 v8, v0
	v_mov_b32_e32 v9, v0
	v_mov_b32_e32 v10, v0
	v_mov_b32_e32 v11, v0
	v_mov_b32_e32 v12, v0
	v_mov_b32_e32 v13, v0
	v_mov_b32_e32 v14, v0
	v_mov_b32_e32 v15, v0
	v_readlane_b32 s9, v253, 61
	s_waitcnt vmcnt(0)
.LBB0_188:
	s_mul_i32 s4, s2, 0xab
	s_add_i32 s5, s4, 0xff55
	s_bfe_u32 s5, s5, 0x6000a
	s_mul_i32 s5, s5, 6
	s_not_b32 s5, s5
	v_lshl_add_u64 v[34:35], v[32:33], 0, s[0:1]
	s_mov_b32 s7, s42
	s_add_i32 s5, s5, s2
	v_add_co_u32_e32 v18, vcc, s7, v34
	s_and_b32 s5, s5, 0xff
	v_cvt_pk_bf16_f32 v16, v0, v1
	v_cvt_pk_bf16_f32 v17, v2, v3
	v_addc_co_u32_e32 v19, vcc, 0, v35, vcc
	s_mulk_i32 s5, 0x4100
	global_store_dwordx2 v[18:19], v[16:17], off
	v_cvt_pk_bf16_f32 v16, v4, v5
	v_cvt_pk_bf16_f32 v17, v6, v7
	global_store_dwordx2 v[18:19], v[16:17], off offset:512
	v_cvt_pk_bf16_f32 v16, v8, v9
	v_cvt_pk_bf16_f32 v17, v10, v11
	s_add_i32 s5, s5, 0
	global_store_dwordx2 v[18:19], v[16:17], off offset:1024
	v_cvt_pk_bf16_f32 v16, v12, v13
	v_cvt_pk_bf16_f32 v17, v14, v15
	s_add_i32 s7, s5, s3
	global_store_dwordx2 v[18:19], v[16:17], off offset:1536
	v_add3_u32 v16, s7, v36, v37
	v_add_u32_e32 v48, s5, v38
	v_add_u32_e32 v52, s5, v39
	ds_read_b128 v[24:27], v16 offset:18432
	ds_read_b128 v[28:31], v16 offset:18464
	ds_read_b128 v[20:23], v16 offset:18496
	ds_read_b128 v[16:19], v16 offset:18528
	ds_read_b128 v[48:51], v48 offset:34816
	ds_read_b64 v[52:53], v52 offset:26624
	s_bfe_u32 s4, s4, 0x6000a
	s_mul_i32 s4, s4, 6
	s_sub_i32 s4, s2, s4
	s_and_b32 s4, s4, 0xff
	s_waitcnt lgkmcnt(0)
	v_lshlrev_b32_e32 v54, 16, v52
	v_and_b32_e32 v55, 0xffff0000, v52
	v_pk_fma_f32 v[0:1], v[0:1], v[48:49], v[54:55]
	v_lshlrev_b32_e32 v48, 16, v53
	v_and_b32_e32 v49, 0xffff0000, v53
	v_pk_fma_f32 v[2:3], v[2:3], v[50:51], v[48:49]
	v_add_u32_e32 v48, s5, v40
	v_add_u32_e32 v52, s5, v41
	ds_read_b128 v[48:51], v48 offset:34816
	ds_read_b64 v[52:53], v52 offset:26624
	s_mulk_i32 s4, 0x4100
	s_add_i32 s4, s4, 0
	s_add_i32 s2, s2, 2
	s_waitcnt lgkmcnt(0)
	v_lshlrev_b32_e32 v54, 16, v52
	v_and_b32_e32 v55, 0xffff0000, v52
	v_pk_fma_f32 v[4:5], v[4:5], v[48:49], v[54:55]
	v_lshlrev_b32_e32 v48, 16, v53
	v_and_b32_e32 v49, 0xffff0000, v53
	v_pk_fma_f32 v[6:7], v[6:7], v[50:51], v[48:49]
	v_add_u32_e32 v48, s5, v42
	v_add_u32_e32 v52, s5, v43
	ds_read_b128 v[48:51], v48 offset:34816
	ds_read_b64 v[52:53], v52 offset:26624
	s_waitcnt lgkmcnt(0)
	v_lshlrev_b32_e32 v54, 16, v52
	v_and_b32_e32 v55, 0xffff0000, v52
	v_pk_fma_f32 v[8:9], v[8:9], v[48:49], v[54:55]
	v_lshlrev_b32_e32 v48, 16, v53
	v_and_b32_e32 v49, 0xffff0000, v53
	v_pk_fma_f32 v[10:11], v[10:11], v[50:51], v[48:49]
	v_add_u32_e32 v48, s5, v44
	v_add_u32_e32 v52, s5, v45
	ds_read_b128 v[48:51], v48 offset:34816
	ds_read_b64 v[52:53], v52 offset:26624
	s_mov_b32 s5, s43
	s_waitcnt lgkmcnt(0)
	v_lshlrev_b32_e32 v54, 16, v52
	v_and_b32_e32 v55, 0xffff0000, v52
	v_pk_fma_f32 v[12:13], v[12:13], v[48:49], v[54:55]
	v_lshlrev_b32_e32 v48, 16, v53
	v_and_b32_e32 v49, 0xffff0000, v53
	v_pk_fma_f32 v[14:15], v[14:15], v[50:51], v[48:49]
	ds_read_b128 v[48:51], v46
	ds_read_b128 v[52:55], v46 offset:32
	s_waitcnt lgkmcnt(1)
	v_mfma_f32_32x32x16_bf16 v[0:15], v[24:27], v[48:51], v[0:15]
	ds_read_b128 v[24:27], v46 offset:64
	s_waitcnt lgkmcnt(1)
	v_mfma_f32_32x32x16_bf16 v[0:15], v[28:31], v[52:55], v[0:15]
	s_waitcnt lgkmcnt(0)
	v_mfma_f32_32x32x16_bf16 v[0:15], v[20:23], v[24:27], v[0:15]
	ds_read_b128 v[20:23], v46 offset:96
	v_add_u32_e32 v24, 0x2000, v47
	s_waitcnt lgkmcnt(0)
	v_mfma_f32_32x32x16_bf16 v[0:15], v[16:19], v[20:23], v[0:15]
	s_nop 11
	v_cvt_pk_bf16_f32 v16, v0, v1
	v_cvt_pk_bf16_f32 v17, v2, v3
	v_cvt_pk_bf16_f32 v18, v4, v5
	v_cvt_pk_bf16_f32 v19, v6, v7
	v_cvt_pk_bf16_f32 v20, v8, v9
	v_cvt_pk_bf16_f32 v21, v10, v11
	v_cvt_pk_bf16_f32 v22, v12, v13
	v_cvt_pk_bf16_f32 v23, v14, v15
	ds_write2_b64 v24, v[16:17], v[18:19] offset0:128 offset1:130
	ds_write2_b64 v24, v[20:21], v[22:23] offset0:132 offset1:134
	v_add_co_u32_e32 v24, vcc, s5, v34
	s_add_i32 s5, s4, s3
	s_nop 0
	v_addc_co_u32_e32 v25, vcc, 0, v35, vcc
	s_waitcnt lgkmcnt(0)
	s_barrier
; __device__ __forceinline__ unsigned cvtpk(float lo, float hi) { f32x2_t v = {lo, hi}; bf16x2_t b = __builtin_convertvector(v, bf16x2_t); return __builtin_bit_cast(unsigned, b); }
; __device__ __forceinline__ float bflo(unsigned w) { return __uint_as_float(w << 16); }
; __device__ __forceinline__ float bfhi(unsigned w) { return __uint_as_float(w & 0xffff0000u); }
; #define SCAN_BAR() do { asm volatile("s_waitcnt lgkmcnt(0)" ::: "memory"); __builtin_amdgcn_s_barrier(); asm volatile("" ::: "memory"); } while (0)
; __device__ __forceinline__ void rwkv_scan(const KA& A, const Ctx& F, int l, int b, int h) {
;     ...
;         for (int j = 0; j < 64; ++j) {
;             const unsigned char* HBc = L + (j & 1) * 9216; unsigned char* HBn = L + ((j + 1) & 1) * 9216;
;             const unsigned char* sb = L + SC_RING + (j % SC_NS) * SC_SLOT;
;             if (wr) {
; #pragma unroll
;                 for (int g4 = 0; g4 < 4; ++g4) { v2u wv; wv.x = cvtpk(Hacc[4 * g4], Hacc[4 * g4 + 1]); wv.y = cvtpk(Hacc[4 * g4 + 2], Hacc[4 * g4 + 3]); *(v2u*)(HS + (size_t)j * 4096 + (((tb2 * 4 + 2 * ta + (g4 >> 1)) * 64 + (g4 & 1) * 32 + r32) << 3) + 4 * hh) = wv; } }
;             bf16x8_t mf[4];
; #pragma unroll
;             for (int s = 0; s < 4; ++s) mf[s] = *(const bf16x8_t*)(sb + ((32 * ta + r32) * 64 + 16 * s + 8 * hh) * 2);
; #pragma unroll
;             for (int g4 = 0; g4 < 4; ++g4) { const int c0 = 32 * ta + 8 * g4 + 4 * hh; const f32x4 gl = *(const f32x4*)(sb + 16384 + c0 * 4); const v2u nv = *(const v2u*)(sb + 8192 + ((32 * tb2 + r32) * 64 + c0) * 2);
;                 Hacc[4 * g4 + 0] = Hacc[4 * g4 + 0] * gl[0] + bflo(nv.x); Hacc[4 * g4 + 1] = Hacc[4 * g4 + 1] * gl[1] + bfhi(nv.x); Hacc[4 * g4 + 2] = Hacc[4 * g4 + 2] * gl[2] + bflo(nv.y); Hacc[4 * g4 + 3] = Hacc[4 * g4 + 3] * gl[3] + bfhi(nv.y); }
; #pragma unroll
;             for (int s = 0; s < 4; ++s) Hacc = __builtin_amdgcn_mfma_f32_32x32x16_bf16(mf[s], ldfrag(HBc, 32 * tb2 + r32, s, hh), Hacc, 0, 0, 0);
;             st_tileT(HBn, 32 * tb2 + r32, 32 * ta, Hacc, hh);
;             SCAN_BAR();
;         }
	global_store_dwordx2 v[24:25], v[16:17], off
	global_store_dwordx2 v[24:25], v[18:19], off offset:512
	global_store_dwordx2 v[24:25], v[20:21], off offset:1024
	global_store_dwordx2 v[24:25], v[22:23], off offset:1536
	v_add3_u32 v28, s5, v36, v37
	v_add_u32_e32 v34, s4, v38
	ds_read_b128 v[16:19], v28 offset:18432
	ds_read_b128 v[20:23], v28 offset:18464
	ds_read_b128 v[24:27], v28 offset:18496
	ds_read_b128 v[28:31], v28 offset:18528
	ds_read_b128 v[48:51], v34 offset:34816
	v_add_u32_e32 v34, s4, v39
	ds_read_b64 v[34:35], v34 offset:26624
	s_add_u32 s0, s0, 0x4000
	s_addc_u32 s1, s1, 0
	s_cmp_eq_u32 s0, 0x80000
	s_waitcnt lgkmcnt(0)
	v_lshlrev_b32_e32 v52, 16, v34
	v_and_b32_e32 v53, 0xffff0000, v34
	v_lshlrev_b32_e32 v34, 16, v35
	v_and_b32_e32 v35, 0xffff0000, v35
	v_pk_fma_f32 v[2:3], v[2:3], v[50:51], v[34:35]
	v_add_u32_e32 v34, s4, v40
	v_pk_fma_f32 v[0:1], v[0:1], v[48:49], v[52:53]
	ds_read_b128 v[48:51], v34 offset:34816
	v_add_u32_e32 v34, s4, v41
	ds_read_b64 v[34:35], v34 offset:26624
	s_waitcnt lgkmcnt(0)
	v_lshlrev_b32_e32 v52, 16, v34
	v_and_b32_e32 v53, 0xffff0000, v34
	v_lshlrev_b32_e32 v34, 16, v35
	v_and_b32_e32 v35, 0xffff0000, v35
	v_pk_fma_f32 v[6:7], v[6:7], v[50:51], v[34:35]
	v_add_u32_e32 v34, s4, v42
	v_pk_fma_f32 v[4:5], v[4:5], v[48:49], v[52:53]
	ds_read_b128 v[48:51], v34 offset:34816
	v_add_u32_e32 v34, s4, v43
	ds_read_b64 v[34:35], v34 offset:26624
	s_waitcnt lgkmcnt(0)
	v_lshlrev_b32_e32 v52, 16, v34
	v_and_b32_e32 v53, 0xffff0000, v34
	v_lshlrev_b32_e32 v34, 16, v35
	v_and_b32_e32 v35, 0xffff0000, v35
	v_pk_fma_f32 v[10:11], v[10:11], v[50:51], v[34:35]
	v_add_u32_e32 v34, s4, v44
	v_pk_fma_f32 v[8:9], v[8:9], v[48:49], v[52:53]
	ds_read_b128 v[48:51], v34 offset:34816
	v_add_u32_e32 v34, s4, v45
	ds_read_b64 v[34:35], v34 offset:26624
	s_waitcnt lgkmcnt(0)
	v_lshlrev_b32_e32 v52, 16, v34
	v_and_b32_e32 v53, 0xffff0000, v34
	v_lshlrev_b32_e32 v34, 16, v35
	v_and_b32_e32 v35, 0xffff0000, v35
	v_pk_fma_f32 v[12:13], v[12:13], v[48:49], v[52:53]
	v_pk_fma_f32 v[14:15], v[14:15], v[50:51], v[34:35]
	ds_read_b128 v[48:51], v46 offset:9216
	ds_read_b128 v[52:55], v46 offset:9248
	s_waitcnt lgkmcnt(1)
	v_mfma_f32_32x32x16_bf16 v[0:15], v[16:19], v[48:51], v[0:15]
	ds_read_b128 v[16:19], v46 offset:9280
	s_waitcnt lgkmcnt(1)
	v_mfma_f32_32x32x16_bf16 v[0:15], v[20:23], v[52:55], v[0:15]
	s_waitcnt lgkmcnt(0)
	v_mfma_f32_32x32x16_bf16 v[0:15], v[24:27], v[16:19], v[0:15]
	ds_read_b128 v[16:19], v46 offset:9312
	s_waitcnt lgkmcnt(0)
	v_mfma_f32_32x32x16_bf16 v[0:15], v[28:31], v[16:19], v[0:15]
	s_nop 11
	v_cvt_pk_bf16_f32 v16, v0, v1
	v_cvt_pk_bf16_f32 v17, v2, v3
	v_cvt_pk_bf16_f32 v18, v4, v5
	v_cvt_pk_bf16_f32 v19, v6, v7
	ds_write2_b64 v47, v[16:17], v[18:19] offset1:2
	v_cvt_pk_bf16_f32 v16, v8, v9
	v_cvt_pk_bf16_f32 v17, v10, v11
	v_cvt_pk_bf16_f32 v18, v12, v13
	v_cvt_pk_bf16_f32 v19, v14, v15
	ds_write2_b64 v47, v[16:17], v[18:19] offset0:4 offset1:6
	s_waitcnt lgkmcnt(0)
	s_barrier
	s_cbranch_scc0 .LBB0_188
	s_mov_b64 s[0:1], 0
; #define LAS __attribute__((address_space(3)))
;     __device__ __forceinline__ unsigned char* ws() const { return *(const __attribute__((address_space(4))) ucptr_t*)(p + 264); }
; #define SCAN_BAR() do { asm volatile("s_waitcnt lgkmcnt(0)" ::: "memory"); __builtin_amdgcn_s_barrier(); asm volatile("" ::: "memory"); } while (0)
; __device__ __forceinline__ void scan_dma(LAS unsigned char* lds, int slot, const bf16* MC, const bf16* NT, const float* GL, int v, int lane) {
;     LAS unsigned char* sb = lds + SC_RING + slot * SC_SLOT;
; #pragma unroll
;     for (int q = 0; q < 2; ++q) {
;         __builtin_amdgcn_global_load_lds((const unsigned*)((const char*)MC + (2 * v + q) * 1024 + lane * 16), (LAS unsigned*)(sb + (2 * v + q) * 1024), 16, 0, 0);
;         __builtin_amdgcn_global_load_lds((const unsigned*)((const char*)NT + (2 * v + q) * 1024 + lane * 16), (LAS unsigned*)(sb + 8192 + (2 * v + q) * 1024), 16, 0, 0); }
;     __builtin_amdgcn_global_load_lds((const unsigned*)((const char*)GL + lane * 4), (LAS unsigned*)(sb + 16384), 4, 0, 0);
; }
; __device__ __forceinline__ void rwkv_scan(const KA& A, const Ctx& F, int l, int b, int h) {
;     ...
;     const bf16* MC = (const bf16*)(F.ws + WS_RMC) + item0 * 4096; const bf16* NT = (const bf16*)(F.ws + WS_RNT) + item0 * 4096; const float* GL = (const float*)(F.ws + WS_RGL) + item0 * 64;
;     const bool wr = !(F.dry && (DRY_SEL & 2));
;     ...
;     if (w >= 4) {
;         const int v = w - 4;
; #pragma unroll
;         for (int p = 0; p < SC_PF; ++p) scan_dma(L3, p, MC + (size_t)p * 4096, NT + (size_t)p * 4096, GL + p * 64, v, lane);
;         asm volatile("s_waitcnt vmcnt(20)" ::: "memory");
;         SCAN_BAR();
.LBB0_190:
	s_and_b64 vcc, exec, s[0:1]
	s_cbranch_vccz .LBB0_197
	v_readlane_b32 s12, v253, 60
	s_lshl_b64 s[2:3], s[40:41], 14
	v_readlane_b32 s14, v253, 62
	v_readlane_b32 s15, v253, 63
	s_add_u32 s10, s14, s2
	s_addc_u32 s11, s15, s3
	s_lshl_b64 s[0:1], s[40:41], 19
	v_readlane_b32 s13, v253, 61
	s_add_u32 s12, s14, s0
	s_addc_u32 s13, s15, s1
	v_readlane_b32 s4, v254, 2
	v_readlane_b32 s5, v254, 3
	s_add_u32 s14, s4, s0
	s_addc_u32 s15, s5, s1
	s_lshl_b32 s8, s6, 11
	v_lshlrev_b32_e32 v80, 4, v114
	v_lshlrev_b32_e32 v4, 2, v114
	v_mov_b32_e32 v5, v81
	s_add_i32 s4, s8, 0xffffe000
	v_lshl_add_u64 v[0:1], s[14:15], 0, v[80:81]
	v_lshl_add_u64 v[2:3], s[12:13], 0, v[80:81]
	s_mov_b32 s5, s24
	v_lshl_add_u64 v[6:7], s[10:11], 0, v[4:5]
	s_mov_b64 s[10:11], 0x1f000000
	s_add_i32 s9, s8, 0
	v_lshl_add_u64 v[8:9], v[6:7], 0, s[10:11]
	v_lshl_add_u64 v[10:11], v[0:1], 0, s[4:5]
	s_add_i32 m0, s9, 0x2800
	v_lshl_add_u64 v[12:13], v[2:3], 0, s[4:5]
	s_mov_b64 s[10:11], 0x1c000000
	global_load_lds_dwordx4 v[10:11], off
	v_lshl_add_u64 v[14:15], v[12:13], 0, s[10:11]
	s_add_i32 m0, s9, 0x4800
	s_mov_b64 s[10:11], 0x400
	global_load_lds_dwordx4 v[14:15], off
	v_lshl_add_u64 v[10:11], v[10:11], 0, s[10:11]
	s_add_i32 m0, s9, 0x2c00
	s_mov_b64 s[10:11], 0x1c000400
	global_load_lds_dwordx4 v[10:11], off
	v_lshl_add_u64 v[10:11], v[12:13], 0, s[10:11]
	s_add_i32 m0, s9, 0x4c00
	v_readlane_b32 s10, v253, 42
	global_load_lds_dwordx4 v[10:11], off
	s_mov_b32 m0, s10
	s_mov_b64 s[10:11], 0x1c002000
	global_load_lds_dword v[8:9], off
	v_lshl_add_u64 v[8:9], v[0:1], 0, s[34:35]
	v_lshl_add_u64 v[10:11], v[2:3], 0, s[10:11]
	v_lshl_add_u64 v[12:13], v[8:9], 0, s[4:5]
	s_add_i32 m0, s9, 0x6900
	s_add_i32 s6, s8, 0xffffe400
	s_mov_b32 s7, s24
	global_load_lds_dwordx4 v[12:13], off
	v_lshl_add_u64 v[12:13], v[10:11], 0, s[4:5]
	s_add_i32 m0, s9, 0x8900
	v_lshl_add_u64 v[8:9], v[8:9], 0, s[6:7]
	global_load_lds_dwordx4 v[12:13], off
	s_add_i32 m0, s9, 0x6d00
	s_mov_b64 s[10:11], 0x1f000100
	global_load_lds_dwordx4 v[8:9], off
	v_lshl_add_u64 v[8:9], v[10:11], 0, s[6:7]
	s_add_i32 m0, s9, 0x8d00
	s_nop 0
	global_load_lds_dwordx4 v[8:9], off
	v_lshl_add_u64 v[8:9], v[6:7], 0, s[10:11]
	v_readlane_b32 s10, v253, 43
	s_mov_b32 m0, s10
	s_mov_b64 s[10:11], 0x4000
	global_load_lds_dword v[8:9], off
	v_lshl_add_u64 v[8:9], v[0:1], 0, s[10:11]
	s_mov_b64 s[10:11], 0x1c004000
	v_lshl_add_u64 v[10:11], v[2:3], 0, s[10:11]
	v_lshl_add_u64 v[12:13], v[8:9], 0, s[4:5]
	s_add_i32 m0, s9, 0xaa00
	v_lshl_add_u64 v[8:9], v[8:9], 0, s[6:7]
	global_load_lds_dwordx4 v[12:13], off
	v_lshl_add_u64 v[12:13], v[10:11], 0, s[4:5]
	s_add_i32 m0, s9, 0xca00
	s_mov_b64 s[10:11], 0x1f000200
	global_load_lds_dwordx4 v[12:13], off
	s_add_i32 m0, s9, 0xae00
	s_nop 0
	global_load_lds_dwordx4 v[8:9], off
	v_lshl_add_u64 v[8:9], v[10:11], 0, s[6:7]
	s_add_i32 m0, s9, 0xce00
	s_nop 0
	global_load_lds_dwordx4 v[8:9], off
	v_lshl_add_u64 v[8:9], v[6:7], 0, s[10:11]
	v_readlane_b32 s10, v253, 44
	s_mov_b32 m0, s10
	s_mov_b64 s[10:11], 0x6000
	global_load_lds_dword v[8:9], off
	v_lshl_add_u64 v[8:9], v[0:1], 0, s[10:11]
	s_mov_b64 s[10:11], 0x1c006000
	v_lshl_add_u64 v[10:11], v[2:3], 0, s[10:11]
	v_lshl_add_u64 v[12:13], v[8:9], 0, s[4:5]
	s_add_i32 m0, s9, 0xeb00
	v_readlane_b32 s10, v253, 45
	global_load_lds_dwordx4 v[12:13], off
	v_lshl_add_u64 v[12:13], v[10:11], 0, s[4:5]
	s_add_i32 m0, s10, s4
	v_lshl_add_u64 v[8:9], v[8:9], 0, s[6:7]
	global_load_lds_dwordx4 v[12:13], off
	s_add_i32 m0, s9, 0xef00
	v_readlane_b32 s9, v253, 46
	global_load_lds_dwordx4 v[8:9], off
	v_lshl_add_u64 v[8:9], v[10:11], 0, s[6:7]
	s_add_i32 m0, s10, s6
	s_mov_b64 s[10:11], 0x1f000300
	global_load_lds_dwordx4 v[8:9], off
	v_lshl_add_u64 v[8:9], v[6:7], 0, s[10:11]
	s_mov_b64 s[10:11], 0x8000
	s_mov_b32 m0, s9
	v_lshl_add_u64 v[0:1], v[0:1], 0, s[10:11]
	s_mov_b64 s[10:11], 0x1c008000
	v_readlane_b32 s9, v253, 47
	global_load_lds_dword v[8:9], off
	v_lshl_add_u64 v[2:3], v[2:3], 0, s[10:11]
	v_lshl_add_u64 v[8:9], v[0:1], 0, s[4:5]
	s_add_i32 m0, s9, s4
	v_lshl_add_u64 v[0:1], v[0:1], 0, s[6:7]
	global_load_lds_dwordx4 v[8:9], off
	v_lshl_add_u64 v[8:9], v[2:3], 0, s[4:5]
	v_readlane_b32 s5, v253, 48
	s_add_i32 m0, s5, s4
	s_nop 0
	global_load_lds_dwordx4 v[8:9], off
	s_add_i32 m0, s9, s6
	s_nop 0
	global_load_lds_dwordx4 v[0:1], off
	v_lshl_add_u64 v[0:1], v[2:3], 0, s[6:7]
	s_add_i32 m0, s5, s6
	s_mov_b64 s[6:7], 0x1f000400
	v_readlane_b32 s5, v253, 49
	global_load_lds_dwordx4 v[0:1], off
	v_lshl_add_u64 v[0:1], v[6:7], 0, s[6:7]
	s_mov_b32 m0, s5
	s_add_u32 s2, s2, 0x1f000500
	global_load_lds_dword v[0:1], off
	s_waitcnt vmcnt(20)
	s_addc_u32 s3, s3, 0
	s_waitcnt lgkmcnt(0)
	s_barrier
	s_add_u32 s0, s4, s0
	s_addc_u32 s1, 0, s1
	v_or_b32_e32 v0, s2, v4
	v_mov_b32_e32 v1, s3
	v_or_b32_e32 v2, s0, v80
	v_mov_b32_e32 v3, s1
	s_mov_b32 s2, 0
	s_branch .LBB0_193

; #define LAS __attribute__((address_space(3)))
; __device__ __forceinline__ float xsum32(float v) { auto r = __builtin_amdgcn_permlane32_swap(__float_as_uint(v), __float_as_uint(v), false, false); return __uint_as_float(r[0]) + __uint_as_float(r[1]); }
; __device__ __forceinline__ int crow16(int g, int hh) { return (g & 3) + 8 * (g >> 2) + 4 * hh; }
; __device__ __forceinline__ void attn_v2(const KA& A, const Ctx& F, int l) {
;     ...
;     const int lane = F.lane, q = lane & 31, hh = lane >> 5, w = F.wave;
;     unsigned* ctr = (unsigned*)(F.ws + WS_CTL) + CW_ATT + 64 * l + ((F.dry && (DRY_SEL & 2)) ? 32 : 0); volatile LAS unsigned* slot = (volatile LAS unsigned*)(F.lds + MISC_OFF + 64);
;     bool first_ = true;
; #pragma unroll 1
;     for (;;) {
;         int item;
;         if (first_) { item = F.bid; first_ = false; }
;         else { if (F.tid == 0) *slot = 256u + __hip_atomic_fetch_add(ctr, 1u, __ATOMIC_RELAXED, __HIP_MEMORY_SCOPE_AGENT);
;                __syncthreads();
;                item = (int)*slot; }
;         if (item >= ATT_ITEMS) break;
;         const int idx16 = item & 15, h = (item >> 4) % 6, b = item / 96;
;     ...
;         const int kbase = i0 + 32 * w - 128;
;         float mx = -3.0e38f;
; #pragma unroll
;         for (int kt = 0; kt < 5; ++kt) {
;             if (kt == 0 || kt == 4 || kbase < 0) {
; #pragma unroll
;                 for (int gq = 0; gq < 16; ++gq) { const int kl = crow16(gq, hh); const int dist = q + 128 - 32 * kt - kl;
;                     const bool ok = (dist >= 0) && (dist <= 128) && (kbase + 32 * kt + kl >= 0);
;                     if (!ok) p[kt][gq] = -3.0e38f; } }
; #pragma unroll
;             for (int gq = 0; gq < 16; ++gq) mx = fmaxf(mx, p[kt][gq]);
;         }
;         mx = xmax32(mx);
;         const float sc = 0.125f * 1.4426950408889634f;
;         float l = 0.f;
; #pragma unroll
;         for (int kt = 0; kt < 5; ++kt)
; #pragma unroll
;             for (int gq = 0; gq < 16; ++gq) { const float e = __builtin_amdgcn_exp2f((p[kt][gq] - mx) * sc); p[kt][gq] = e; l += e; }
;         l = xsum32(l);
;         asm volatile("s_waitcnt lgkmcnt(0)" ::: "memory"); __builtin_amdgcn_s_barrier(); asm volatile("" ::: "memory");
;         f32x16 o[2]; o[0] = f32x16{}; o[1] = f32x16{};
;         const unsigned char* vb = VI + ((32 * w + 4 * hh + ((lane & 15) >> 2)) * ATT_VS + 16 * ((lane >> 4) & 1) + 4 * (lane & 3)) * 2;
.LBB0_197:
	s_lshl_b32 s2, s79, 6
	v_readlane_b32 s8, v253, 60
	s_ashr_i32 s3, s2, 31
	v_readlane_b32 s10, v253, 62
	v_mov_b32_e32 v1, v242
	v_readlane_b32 s11, v253, 63
	s_add_u32 s0, s10, 0x1a400000
	s_waitcnt vmcnt(0) lgkmcnt(0)
	s_barrier
	s_addc_u32 s1, s11, 0
	v_and_b32_e32 v142, 31, v1
	v_bfe_u32 v3, v1, 5, 1
	s_lshl_b64 s[2:3], s[2:3], 2
	v_and_b32_e32 v2, 63, v1
	s_add_u32 s2, s10, s2
	v_lshlrev_b32_e32 v0, 3, v3
	v_lshlrev_b32_e32 v143, 2, v3
	v_or_b32_e32 v3, 0x80, v142
	s_addc_u32 s3, s11, s3
	v_cmp_gt_u32_e64 s[38:39], 32, v2
	v_sub_u32_e32 v2, v3, v143
	s_movk_i32 s6, 0x81
	s_add_u32 s16, s2, 0x1000
	v_cmp_gt_u32_e64 s[40:41], s6, v2
	v_sub_u32_e32 v2, v143, v3
	s_movk_i32 s2, 0xff7e
	v_or_b32_e32 v144, 2, v143
	v_cmp_lt_u32_e64 s[42:43], s2, v2
	v_sub_u32_e32 v2, v3, v144
	v_or_b32_e32 v145, 3, v143
	v_cmp_gt_u32_e64 s[44:45], s6, v2
	v_sub_u32_e32 v2, v3, v145
	v_or_b32_e32 v146, 8, v143
	v_cmp_gt_u32_e64 s[46:47], s6, v2
	v_sub_u32_e32 v2, v3, v146
	v_or_b32_e32 v147, 9, v143
	v_cmp_gt_u32_e64 s[48:49], s6, v2
	v_sub_u32_e32 v2, v3, v147
	v_or_b32_e32 v148, 10, v143
	v_cmp_gt_u32_e64 s[50:51], s6, v2
	v_sub_u32_e32 v2, v3, v148
	v_or_b32_e32 v149, 11, v143
	v_cmp_gt_u32_e64 s[52:53], s6, v2
	v_sub_u32_e32 v2, v3, v149
	v_or_b32_e32 v150, 16, v143
	v_cmp_gt_u32_e64 s[54:55], s6, v2
	v_sub_u32_e32 v2, v3, v150
	v_or_b32_e32 v151, 17, v143
	v_cmp_gt_u32_e64 s[56:57], s6, v2
	v_sub_u32_e32 v2, v3, v151
	v_or_b32_e32 v152, 18, v143
	v_cmp_gt_u32_e64 s[58:59], s6, v2
	v_sub_u32_e32 v2, v3, v152
	v_or_b32_e32 v153, 19, v143
	v_cmp_gt_u32_e64 s[60:61], s6, v2
	v_sub_u32_e32 v2, v3, v153
	v_or_b32_e32 v154, 24, v143
	v_cmp_gt_u32_e64 s[62:63], s6, v2
	v_sub_u32_e32 v2, v3, v154
	v_or_b32_e32 v155, 25, v143
	v_cmp_gt_u32_e64 s[64:65], s6, v2
	v_sub_u32_e32 v2, v3, v155
	v_or_b32_e32 v156, 26, v143
	v_cmp_gt_u32_e64 s[66:67], s6, v2
	v_sub_u32_e32 v2, v3, v156
	v_or_b32_e32 v157, 27, v143
	v_cmp_gt_u32_e64 s[68:69], s6, v2
	v_sub_u32_e32 v2, v3, v157
	v_cmp_gt_u32_e64 s[70:71], s6, v2
	v_sub_u32_e32 v2, v142, v143
	v_sub_u32_e32 v3, v143, v142
	v_cmp_lt_u32_e64 s[74:75], s2, v3
	v_add_u32_e32 v3, -2, v2
	v_cmp_gt_u32_e64 s[76:77], s6, v3
	v_add_u32_e32 v3, -3, v2
	v_writelane_b32 v254, s79, 6
	v_cmp_gt_u32_e64 s[78:79], s6, v3
	v_add_u32_e32 v3, -8, v2
	v_cmp_gt_u32_e64 s[80:81], s6, v3
	v_add_u32_e32 v3, -9, v2
	v_cmp_gt_u32_e64 s[26:27], s6, v3
	v_add_u32_e32 v3, -10, v2
	v_cmp_gt_u32_e64 s[84:85], s6, v3
	v_add_u32_e32 v3, -11, v2
	v_cmp_gt_u32_e64 s[86:87], s6, v3
	v_add_u32_e32 v3, -16, v2
	v_cmp_gt_u32_e64 s[88:89], s6, v3
	v_subrev_u32_e32 v3, 17, v2
	v_readfirstlane_b32 s4, v1
	v_cmp_gt_u32_e64 s[90:91], s6, v3
	v_subrev_u32_e32 v3, 18, v2
	s_addc_u32 s17, s3, 0
	v_readlane_b32 s33, v253, 55
	s_nop 1
	s_and_b32 s13, s33, 7
	s_lshl_b32 s12, s13, 2
	s_add_u32 s16, s16, s12
	s_addc_u32 s17, s17, 0
	s_mulk_i32 s13, 0x60
	s_lshr_b32 s12, s33, 3
	s_add_i32 s12, s12, s13
	s_addk_i32 s13, 32
	s_nop 0
	v_writelane_b32 v255, s13, 48
	s_ashr_i32 s33, s4, 1
	v_cmp_gt_u32_e64 s[92:93], s6, v3
	v_subrev_u32_e32 v3, 19, v2
	s_andn2_b32 s33, s33, 31
	v_bfe_u32 v4, v1, 2, 2
	v_cmp_gt_u32_e64 s[94:95], s6, v3
	v_subrev_u32_e32 v3, 24, v2
	v_readlane_b32 s9, v253, 61
	v_or3_b32 v4, v4, v143, s33
	s_movk_i32 s10, 0x60
	v_lshlrev_b32_e32 v6, 2, v1
	v_cmp_gt_u32_e64 s[96:97], s6, v3
	v_subrev_u32_e32 v3, 25, v2
	v_mul_lo_u32 v4, v4, s10
	v_and_b32_e32 v5, 16, v1
	v_and_b32_e32 v6, 12, v6
	v_cmp_gt_u32_e64 s[72:73], s6, v2
	v_cmp_gt_u32_e64 s[2:3], s6, v3
	v_subrev_u32_e32 v3, 26, v2
	v_subrev_u32_e32 v2, 27, v2
	v_or_b32_e32 v173, 0xffffffe0, v1
	v_cmp_eq_u32_e64 s[8:9], 0, v1
	v_ashrrev_i32_e32 v174, 3, v1
	v_lshlrev_b32_e32 v1, 3, v1
	v_or3_b32 v4, v4, v5, v6
	v_cmp_gt_u32_e64 s[4:5], s6, v3
	v_cmp_gt_u32_e64 s[6:7], s6, v2
	v_and_b32_e32 v2, 56, v1
	v_mul_lo_u32 v1, v174, s10
	v_readlane_b32 s10, v253, 55
	s_nop 1
	v_lshlrev_b32_e32 v4, 1, v4
	v_add_lshl_u32 v1, v1, v2, 1
	v_writelane_b32 v255, s10, 38
	v_xor_b32_e32 v158, -9, v143
	v_xor_b32_e32 v159, -10, v143
	v_xor_b32_e32 v160, -11, v143
	v_xor_b32_e32 v161, -12, v143
	v_xor_b32_e32 v162, 0xffffffef, v143
	v_xor_b32_e32 v163, 0xffffffee, v143
	v_xor_b32_e32 v164, 0xffffffed, v143
	v_xor_b32_e32 v165, 0xffffffec, v143
	v_xor_b32_e32 v166, 0xffffffe7, v143
	v_xor_b32_e32 v167, 0xffffffe6, v143
	v_xor_b32_e32 v168, 0xffffffe5, v143
	v_xor_b32_e32 v169, 0xffffffe4, v143
	v_or_b32_e32 v170, 0xffffff80, v142
	v_or_b32_e32 v171, 0xffffffa0, v142
	v_or_b32_e32 v172, 0xffffffc0, v142
	v_add_u32_e32 v175, 0xffffff80, v174
	v_lshlrev_b32_e32 v134, 1, v2
	v_lshlrev_b32_e32 v136, 1, v0
	v_add_u32_e32 v176, 0, v1
	v_add_u32_e32 v177, 0, v4
	v_writelane_b32 v255, s11, 39
	s_branch .LBB0_201
.LBB0_198:
	s_or_b64 exec, exec, s[12:13]
	s_nop 0
	v_readfirstlane_b32 s12, v1
	s_nop 1
	v_add_u32_e32 v0, s12, v0
	v_readlane_b32 s12, v255, 48
	v_cmp_gt_u32_e32 vcc, 64, v0
	s_nop 0
	v_add_u32_e32 v0, s12, v0
	v_mov_b32_e32 v1, 0x300
	v_cndmask_b32_e32 v0, v1, v0, vcc
	v_readlane_b32 s12, v253, 50
	s_nop 1
	v_mov_b32_e32 v1, s12
	ds_write_b32 v1, v0

; __global__ void __launch_bounds__(NTHREADS, 2) mega_fwd(Args args) {
;     ...
;         if (ph + 1 < args.ph_hi) {
;     ...
;             for (int e_ = 0; e_ < EXTRA_SYNCS; ++e_) { XcdBarrier b2 = bar; asm volatile("" : "+s"(b2.bar)); int tb_; asm volatile("v_mbcnt_lo_u32_b32 %0, -1, 0\n\tv_mbcnt_hi_u32_b32 %0, -1, %0\n\tv_or_b32 %0, %1, %0" : "=&v"(tb_) : "s"(wv0 << 6)); xcd_barrier(b2, tb_); }
;     ...
;             if (args.ph_lo < 0) { __threadfence(); cg::this_grid().sync(); }
;             { XcdBarrier b2 = bar; asm volatile("" : "+s"(b2.bar)); int tb_; asm volatile("v_mbcnt_lo_u32_b32 %0, -1, 0\n\tv_mbcnt_hi_u32_b32 %0, -1, %0\n\tv_or_b32 %0, %1, %0" : "=&v"(tb_) : "s"(wv0 << 6)); xcd_barrier(b2, tb_); } }
.LBB0_552:
	s_andn2_saveexec_b64 s[4:5], s[4:5]
	s_cbranch_execz .LBB0_8
	s_add_i32 s4, s70, -2
	s_cmp_lt_u32 s4, 15
	s_cbranch_scc0 .Lxb_global
	s_lshr_b32 s5, 0x73f3, s4
	s_and_b32 s5, s5, 1
	s_cbranch_scc0 .Lxb_global
	v_readfirstlane_b32 s5, v18
	s_cmp_eq_u32 s5, 0
	s_cbranch_scc0 .Lxb_global
	s_mov_b64 s[0:1], exec
	s_branch .LBB0_7
